# ring4+R4 + attn-finish phase processes 2 rows per iteration (8 loads in flight)
# baseline (speedup 1.0000x reference)
.Lfin2_check:
	v_add_u32_e32 v72, s74, v0
	v_cmp_gt_i32_e32 vcc, s0, v72
	s_nop 4
	s_cbranch_vccz .LBB0_189
	v_ashrrev_i32_e32 v1, 31, v0
	v_lshlrev_b64 v[24:25], 12, v[0:1]
	v_lshl_add_u64 v[36:37], v[2:3], 0, v[24:25]
	global_load_dwordx4 v[24:27], v[36:37], off offset:16
	global_load_dwordx4 v[28:31], v[36:37], off
	global_load_dwordx4 v[32:35], v[36:37], off offset:272
	global_load_dwordx4 v[36:39], v[36:37], off offset:256
	v_ashrrev_i32_e32 v73, 31, v72
	v_lshlrev_b64 v[50:51], 12, v[72:73]
	v_lshl_add_u64 v[62:63], v[2:3], 0, v[50:51]
	global_load_dwordx4 v[50:53], v[62:63], off offset:16
	global_load_dwordx4 v[54:57], v[62:63], off
	global_load_dwordx4 v[58:61], v[62:63], off offset:272
	global_load_dwordx4 v[62:65], v[62:63], off offset:256
	s_waitcnt vmcnt(6)
	v_lshlrev_b32_e32 v40, 16, v28
	v_and_b32_e32 v28, 0xffff0000, v28
	s_waitcnt vmcnt(4)
	v_lshlrev_b32_e32 v41, 16, v36
	v_and_b32_e32 v36, 0xffff0000, v36
	v_fma_f32 v40, -v6, v41, v40
	v_fma_f32 v36, -v6, v36, v28
	v_lshlrev_b32_e32 v28, 16, v29
	v_lshlrev_b32_e32 v41, 16, v37
	v_fma_f32 v41, -v6, v41, v28
	v_and_b32_e32 v28, 0xffff0000, v29
	v_and_b32_e32 v29, 0xffff0000, v37
	v_mul_f32_e32 v44, v36, v36
	v_fma_f32 v37, -v6, v29, v28
	v_lshlrev_b32_e32 v28, 16, v30
	v_lshlrev_b32_e32 v29, 16, v38
	v_fmac_f32_e32 v44, v40, v40
	v_fma_f32 v42, -v6, v29, v28
	v_and_b32_e32 v28, 0xffff0000, v30
	v_and_b32_e32 v29, 0xffff0000, v38
	v_fmac_f32_e32 v44, v41, v41
	v_fma_f32 v38, -v6, v29, v28
	v_lshlrev_b32_e32 v28, 16, v31
	v_lshlrev_b32_e32 v29, 16, v39
	v_fmac_f32_e32 v44, v37, v37
	v_fma_f32 v43, -v6, v29, v28
	v_and_b32_e32 v28, 0xffff0000, v31
	v_and_b32_e32 v29, 0xffff0000, v39
	v_fmac_f32_e32 v44, v42, v42
	v_fma_f32 v39, -v6, v29, v28
	v_fmac_f32_e32 v44, v38, v38
	v_and_b32_e32 v28, 0xffff0000, v24
	v_lshlrev_b32_e32 v29, 16, v24
	v_and_b32_e32 v30, 0xffff0000, v32
	v_lshlrev_b32_e32 v31, 16, v32
	v_fmac_f32_e32 v44, v43, v43
	v_pk_fma_f32 v[28:29], v[6:7], v[30:31], v[28:29] neg_lo:[1,0,0] neg_hi:[1,0,0]
	v_fmac_f32_e32 v44, v39, v39
	v_pk_mul_f32 v[30:31], v[28:29], v[28:29]
	s_nop 0
	v_add_f32_e32 v24, v31, v44
	v_add_f32_e32 v32, v30, v24
	v_and_b32_e32 v24, 0xffff0000, v25
	v_lshlrev_b32_e32 v25, 16, v25
	v_and_b32_e32 v30, 0xffff0000, v33
	v_lshlrev_b32_e32 v31, 16, v33
	v_pk_fma_f32 v[30:31], v[6:7], v[30:31], v[24:25] neg_lo:[1,0,0] neg_hi:[1,0,0]
	v_lshlrev_b32_e32 v33, 16, v34
	v_pk_mul_f32 v[24:25], v[30:31], v[30:31]
	s_nop 0
	v_add_f32_e32 v25, v25, v32
	v_add_f32_e32 v44, v24, v25
	v_and_b32_e32 v24, 0xffff0000, v26
	v_lshlrev_b32_e32 v25, 16, v26
	v_and_b32_e32 v32, 0xffff0000, v34
	v_pk_fma_f32 v[32:33], v[6:7], v[32:33], v[24:25] neg_lo:[1,0,0] neg_hi:[1,0,0]
	v_and_b32_e32 v26, 0xffff0000, v35
	v_pk_mul_f32 v[24:25], v[32:33], v[32:33]
	s_nop 0
	v_add_f32_e32 v25, v25, v44
	v_add_f32_e32 v44, v24, v25
	v_and_b32_e32 v24, 0xffff0000, v27
	v_lshlrev_b32_e32 v25, 16, v27
	v_lshlrev_b32_e32 v27, 16, v35
	v_pk_fma_f32 v[34:35], v[6:7], v[26:27], v[24:25] neg_lo:[1,0,0] neg_hi:[1,0,0]
	s_nop 0
	v_pk_mul_f32 v[24:25], v[34:35], v[34:35]
	s_nop 0
	v_add_f32_e32 v25, v25, v44
	v_add_f32_e32 v24, v24, v25
	ds_swizzle_b32 v25, v24 offset:swizzle(SWAP,1)
	s_waitcnt lgkmcnt(0)
	v_add_f32_e32 v24, v24, v25
	ds_swizzle_b32 v25, v24 offset:swizzle(SWAP,2)
	s_waitcnt lgkmcnt(0)
	v_add_f32_e32 v24, v24, v25
	ds_swizzle_b32 v25, v24 offset:swizzle(SWAP,4)
	s_waitcnt lgkmcnt(0)
	v_add_f32_e32 v24, v24, v25
	v_fmamk_f32 v24, v24, 0x3c000000, v169
	v_cmp_gt_f32_e32 vcc, s85, v24
	v_mul_f32_e32 v25, 0x4b800000, v24
	s_nop 0
	v_cndmask_b32_e32 v24, v24, v25, vcc
	v_rsq_f32_e32 v24, v24
	s_nop 0
	v_mul_f32_e32 v25, 0x45800000, v24
	v_cndmask_b32_e32 v44, v24, v25, vcc
	v_mul_f32_e32 v24, v40, v44
	v_mul_f32_e32 v25, v36, v44
	v_mul_f32_e32 v24, v8, v24
	v_mul_f32_e32 v25, v9, v25
	v_cvt_pk_bf16_f32 v24, v24, v25
	v_mul_f32_e32 v25, v29, v44
	v_mul_f32_e32 v26, v28, v44
	v_mul_f32_e32 v25, v16, v25
	v_mul_f32_e32 v26, v17, v26
	v_cvt_pk_bf16_f32 v28, v25, v26
	v_mul_f32_e32 v25, v41, v44
	v_mul_f32_e32 v26, v37, v44
	v_mul_f32_e32 v25, v10, v25
	v_mul_f32_e32 v26, v11, v26
	v_cvt_pk_bf16_f32 v25, v25, v26
	v_mul_f32_e32 v26, v31, v44
	v_mul_f32_e32 v27, v30, v44
	v_mul_f32_e32 v26, v18, v26
	v_mul_f32_e32 v27, v19, v27
	v_cvt_pk_bf16_f32 v29, v26, v27
	v_mul_f32_e32 v26, v42, v44
	v_mul_f32_e32 v27, v38, v44
	v_mul_f32_e32 v26, v12, v26
	v_mul_f32_e32 v27, v13, v27
	v_cvt_pk_bf16_f32 v26, v26, v27
	v_mul_f32_e32 v27, v33, v44
	v_mul_f32_e32 v30, v32, v44
	v_mul_f32_e32 v27, v20, v27
	v_mul_f32_e32 v30, v21, v30
	v_cvt_pk_bf16_f32 v30, v27, v30
	v_mul_f32_e32 v27, v43, v44
	v_mul_f32_e32 v31, v39, v44
	v_mul_f32_e32 v27, v14, v27
	v_mul_f32_e32 v31, v15, v31
	v_cvt_pk_bf16_f32 v27, v27, v31
	v_mul_f32_e32 v31, v35, v44
	v_mul_f32_e32 v32, v34, v44
	v_mul_f32_e32 v31, v22, v31
	v_mul_f32_e32 v32, v23, v32
	v_cvt_pk_bf16_f32 v31, v31, v32
	v_lshlrev_b64 v[32:33], 11, v[0:1]
	v_lshl_add_u64 v[32:33], v[4:5], 0, v[32:33]
	s_waitcnt vmcnt(2)
	v_lshlrev_b32_e32 v66, 16, v54
	v_and_b32_e32 v54, 0xffff0000, v54
	s_waitcnt vmcnt(0)
	v_lshlrev_b32_e32 v67, 16, v62
	v_and_b32_e32 v62, 0xffff0000, v62
	v_fma_f32 v66, -v6, v67, v66
	v_fma_f32 v62, -v6, v62, v54
	v_lshlrev_b32_e32 v54, 16, v55
	v_lshlrev_b32_e32 v67, 16, v63
	v_fma_f32 v67, -v6, v67, v54
	v_and_b32_e32 v54, 0xffff0000, v55
	v_and_b32_e32 v55, 0xffff0000, v63
	v_mul_f32_e32 v70, v62, v62
	v_fma_f32 v63, -v6, v55, v54
	v_lshlrev_b32_e32 v54, 16, v56
	v_lshlrev_b32_e32 v55, 16, v64
	v_fmac_f32_e32 v70, v66, v66
	v_fma_f32 v68, -v6, v55, v54
	v_and_b32_e32 v54, 0xffff0000, v56
	v_and_b32_e32 v55, 0xffff0000, v64
	v_fmac_f32_e32 v70, v67, v67
	v_fma_f32 v64, -v6, v55, v54
	v_lshlrev_b32_e32 v54, 16, v57
	v_lshlrev_b32_e32 v55, 16, v65
	v_fmac_f32_e32 v70, v63, v63
	v_fma_f32 v69, -v6, v55, v54
	v_and_b32_e32 v54, 0xffff0000, v57
	v_and_b32_e32 v55, 0xffff0000, v65
	v_fmac_f32_e32 v70, v68, v68
	v_fma_f32 v65, -v6, v55, v54
	v_fmac_f32_e32 v70, v64, v64
	v_and_b32_e32 v54, 0xffff0000, v50
	v_lshlrev_b32_e32 v55, 16, v50
	v_and_b32_e32 v56, 0xffff0000, v58
	v_lshlrev_b32_e32 v57, 16, v58
	v_fmac_f32_e32 v70, v69, v69
	v_pk_fma_f32 v[54:55], v[6:7], v[56:57], v[54:55] neg_lo:[1,0,0] neg_hi:[1,0,0]
	v_fmac_f32_e32 v70, v65, v65
	v_pk_mul_f32 v[56:57], v[54:55], v[54:55]
	s_nop 0
	v_add_f32_e32 v50, v57, v70
	v_add_f32_e32 v58, v56, v50
	v_and_b32_e32 v50, 0xffff0000, v51
	v_lshlrev_b32_e32 v51, 16, v51
	v_and_b32_e32 v56, 0xffff0000, v59
	v_lshlrev_b32_e32 v57, 16, v59
	v_pk_fma_f32 v[56:57], v[6:7], v[56:57], v[50:51] neg_lo:[1,0,0] neg_hi:[1,0,0]
	v_lshlrev_b32_e32 v59, 16, v60
	v_pk_mul_f32 v[50:51], v[56:57], v[56:57]
	s_nop 0
	v_add_f32_e32 v51, v51, v58
	v_add_f32_e32 v70, v50, v51
	v_and_b32_e32 v50, 0xffff0000, v52
	v_lshlrev_b32_e32 v51, 16, v52
	v_and_b32_e32 v58, 0xffff0000, v60
	v_pk_fma_f32 v[58:59], v[6:7], v[58:59], v[50:51] neg_lo:[1,0,0] neg_hi:[1,0,0]
	v_and_b32_e32 v52, 0xffff0000, v61
	v_pk_mul_f32 v[50:51], v[58:59], v[58:59]
	s_nop 0
	v_add_f32_e32 v51, v51, v70
	v_add_f32_e32 v70, v50, v51
	v_and_b32_e32 v50, 0xffff0000, v53
	v_lshlrev_b32_e32 v51, 16, v53
	v_lshlrev_b32_e32 v53, 16, v61
	v_pk_fma_f32 v[60:61], v[6:7], v[52:53], v[50:51] neg_lo:[1,0,0] neg_hi:[1,0,0]
	s_nop 0
	v_pk_mul_f32 v[50:51], v[60:61], v[60:61]
	s_nop 0
	v_add_f32_e32 v51, v51, v70
	v_add_f32_e32 v50, v50, v51
	ds_swizzle_b32 v51, v50 offset:swizzle(SWAP,1)
	s_waitcnt lgkmcnt(0)
	v_add_f32_e32 v50, v50, v51
	ds_swizzle_b32 v51, v50 offset:swizzle(SWAP,2)
	s_waitcnt lgkmcnt(0)
	v_add_f32_e32 v50, v50, v51
	ds_swizzle_b32 v51, v50 offset:swizzle(SWAP,4)
	s_waitcnt lgkmcnt(0)
	v_add_f32_e32 v50, v50, v51
	v_fmamk_f32 v50, v50, 0x3c000000, v169
	v_cmp_gt_f32_e32 vcc, s85, v50
	v_mul_f32_e32 v51, 0x4b800000, v50
	s_nop 0
	v_cndmask_b32_e32 v50, v50, v51, vcc
	v_rsq_f32_e32 v50, v50
	s_nop 0
	v_mul_f32_e32 v51, 0x45800000, v50
	v_cndmask_b32_e32 v70, v50, v51, vcc
	v_mul_f32_e32 v50, v66, v70
	v_mul_f32_e32 v51, v62, v70
	v_mul_f32_e32 v50, v8, v50
	v_mul_f32_e32 v51, v9, v51
	v_cvt_pk_bf16_f32 v50, v50, v51
	v_mul_f32_e32 v51, v55, v70
	v_mul_f32_e32 v52, v54, v70
	v_mul_f32_e32 v51, v16, v51
	v_mul_f32_e32 v52, v17, v52
	v_cvt_pk_bf16_f32 v54, v51, v52
	v_mul_f32_e32 v51, v67, v70
	v_mul_f32_e32 v52, v63, v70
	v_mul_f32_e32 v51, v10, v51
	v_mul_f32_e32 v52, v11, v52
	v_cvt_pk_bf16_f32 v51, v51, v52
	v_mul_f32_e32 v52, v57, v70
	v_mul_f32_e32 v53, v56, v70
	v_mul_f32_e32 v52, v18, v52
	v_mul_f32_e32 v53, v19, v53
	v_cvt_pk_bf16_f32 v55, v52, v53
	v_mul_f32_e32 v52, v68, v70
	v_mul_f32_e32 v53, v64, v70
	v_mul_f32_e32 v52, v12, v52
	v_mul_f32_e32 v53, v13, v53
	v_cvt_pk_bf16_f32 v52, v52, v53
	v_mul_f32_e32 v53, v59, v70
	v_mul_f32_e32 v56, v58, v70
	v_mul_f32_e32 v53, v20, v53
	v_mul_f32_e32 v56, v21, v56
	v_cvt_pk_bf16_f32 v56, v53, v56
	v_mul_f32_e32 v53, v69, v70
	v_mul_f32_e32 v57, v65, v70
	v_mul_f32_e32 v53, v14, v53
	v_mul_f32_e32 v57, v15, v57
	v_cvt_pk_bf16_f32 v53, v53, v57
	v_mul_f32_e32 v57, v61, v70
	v_mul_f32_e32 v58, v60, v70
	v_mul_f32_e32 v57, v22, v57
	v_mul_f32_e32 v58, v23, v58
	v_cvt_pk_bf16_f32 v57, v57, v58
	v_lshlrev_b64 v[58:59], 11, v[72:73]
	v_lshl_add_u64 v[58:59], v[4:5], 0, v[58:59]
	global_store_dwordx4 v[58:59], v[50:53], off
	global_store_dwordx4 v[58:59], v[54:57], off offset:16
	global_store_dwordx4 v[32:33], v[24:27], off
	global_store_dwordx4 v[32:33], v[28:31], off offset:16
	v_add_u32_e32 v0, s74, v72
	v_cmp_gt_i32_e32 vcc, s0, v0
	s_nop 4
	s_cbranch_vccnz .Lfin2_check
	s_branch .LBB0_190
